# attention K/V staging writes: second V and second K write of a tile reuse the first write's address register with a +8192 immediate (2 address adds per tile gone); doubled vmcnt wait dropped
# baseline (speedup 1.0000x reference)
.LBB0_425:
	ds_read_b64_tr_b16 v[202:203], v199 offset:0x600
	ds_read_b64_tr_b16 v[204:205], v199 offset:0x700
	ds_read_b64_tr_b16 v[206:207], v199 offset:0x1600
	ds_read_b64_tr_b16 v[208:209], v199 offset:0x1700
	ds_read_b64_tr_b16 v[210:211], v199 offset:0x2600
	ds_read_b64_tr_b16 v[212:213], v199 offset:0x2700
	ds_read_b64_tr_b16 v[222:223], v199 offset:0x3600
	ds_read_b64_tr_b16 v[224:225], v199 offset:0x3700
	s_add_i32 s4, s19, 1
	s_cmp_lg_u32 s19, 2
	s_cselect_b32 s18, s4, 0
	s_waitcnt lgkmcnt(6)
	v_mfma_f32_32x32x16_bf16 v[16:31], v[64:67], v[202:205], v[16:31]
	s_lshl_b32 s4, s18, 14
	s_add_i32 s17, s4, 16
	v_add_u32_e32 v64, s17, v184
	s_waitcnt vmcnt(4)
	ds_write_b128 v64, v[132:135]
	ds_write_b128 v64, v[140:143] offset:8192
	s_waitcnt lgkmcnt(6)
	v_mfma_f32_32x32x16_bf16 v[16:31], v[72:75], v[206:209], v[16:31]
	v_add_u32_e32 v64, s17, v183
	ds_write_b128 v64, v[128:131] offset:49152
	s_mov_b64 vcc, s[100:101]
	ds_write_b128 v64, v[136:139] offset:57344
	s_waitcnt lgkmcnt(6)
	v_mfma_f32_32x32x16_bf16 v[16:31], v[68:71], v[210:213], v[16:31]
	s_waitcnt lgkmcnt(4)
	v_mfma_f32_32x32x16_bf16 v[16:31], v[76:79], v[222:225], v[16:31]
	s_cbranch_vccz .LBB0_429
	s_and_saveexec_b64 s[4:5], s[0:1]
	ds_write_b32 v179, v200 offset:128
	s_or_b64 exec, exec, s[4:5]
	s_waitcnt lgkmcnt(0)
	v_add_u32_e32 v76, v177, v176
	ds_read_b128 v[64:67], v76 offset:224
	ds_read_b128 v[68:71], v76 offset:192
	ds_read_b128 v[72:75], v76 offset:160
	ds_read_b128 v[76:79], v76 offset:128
	s_waitcnt lgkmcnt(3)
	v_pk_mul_f32 v[12:13], v[12:13], v[64:65]
	s_waitcnt lgkmcnt(2)
	v_pk_mul_f32 v[8:9], v[8:9], v[68:69]
	s_waitcnt lgkmcnt(1)
	v_pk_mul_f32 v[4:5], v[4:5], v[72:73]
	v_pk_mul_f32 v[14:15], v[14:15], v[66:67]
	v_pk_mul_f32 v[10:11], v[10:11], v[70:71]
	v_pk_mul_f32 v[6:7], v[6:7], v[74:75]
	s_waitcnt lgkmcnt(0)
	v_pk_mul_f32 v[2:3], v[2:3], v[78:79]
	v_pk_mul_f32 v[0:1], v[0:1], v[76:77]
	v_pk_mul_f32 v[60:61], v[60:61], v[64:65]
	v_pk_mul_f32 v[56:57], v[56:57], v[68:69]
	v_pk_mul_f32 v[52:53], v[52:53], v[72:73]
	v_pk_mul_f32 v[62:63], v[62:63], v[66:67]
	v_pk_mul_f32 v[58:59], v[58:59], v[70:71]
	v_pk_mul_f32 v[54:55], v[54:55], v[74:75]
	v_pk_mul_f32 v[50:51], v[50:51], v[78:79]
	v_pk_mul_f32 v[48:49], v[48:49], v[76:77]
	v_pk_mul_f32 v[44:45], v[44:45], v[64:65]
	v_pk_mul_f32 v[40:41], v[40:41], v[68:69]
	v_pk_mul_f32 v[36:37], v[36:37], v[72:73]
	v_pk_mul_f32 v[46:47], v[46:47], v[66:67]
	v_pk_mul_f32 v[42:43], v[42:43], v[70:71]
	v_pk_mul_f32 v[38:39], v[38:39], v[74:75]
	v_pk_mul_f32 v[34:35], v[34:35], v[78:79]
	v_pk_mul_f32 v[32:33], v[32:33], v[76:77]
	v_pk_mul_f32 v[28:29], v[28:29], v[64:65]
	v_pk_mul_f32 v[24:25], v[24:25], v[68:69]
	v_pk_mul_f32 v[20:21], v[20:21], v[72:73]
	v_pk_mul_f32 v[30:31], v[30:31], v[66:67]
	v_pk_mul_f32 v[26:27], v[26:27], v[70:71]
	v_pk_mul_f32 v[22:23], v[22:23], v[74:75]
	v_pk_mul_f32 v[18:19], v[18:19], v[78:79]
	v_pk_mul_f32 v[16:17], v[16:17], v[76:77]

.LBB0_432:
	ds_read_b64_tr_b16 v[204:205], v203 offset:0x600
	ds_read_b64_tr_b16 v[206:207], v203 offset:0x700
	ds_read_b64_tr_b16 v[208:209], v203 offset:0x1600
	ds_read_b64_tr_b16 v[210:211], v203 offset:0x1700
	ds_read_b64_tr_b16 v[222:223], v203 offset:0x2600
	ds_read_b64_tr_b16 v[224:225], v203 offset:0x2700
	ds_read_b64_tr_b16 v[226:227], v203 offset:0x3600
	ds_read_b64_tr_b16 v[228:229], v203 offset:0x3700
	s_add_i32 s16, s18, 1
	s_cmp_lg_u32 s18, 2
	s_cselect_b32 s19, s16, 0
	s_waitcnt lgkmcnt(6)
	v_mfma_f32_32x32x16_bf16 v[16:31], v[88:91], v[204:207], v[16:31]
	s_lshl_b32 s16, s19, 14
	s_add_i32 s16, s16, 16
	s_waitcnt vmcnt(4)
	v_add_u32_e32 v88, s16, v184
	ds_write_b128 v88, v[144:147]
	s_mov_b64 vcc, s[100:101]
	s_waitcnt lgkmcnt(5)
	v_mfma_f32_32x32x16_bf16 v[16:31], v[92:95], v[208:211], v[16:31]
	s_waitcnt lgkmcnt(3)
	v_mfma_f32_32x32x16_bf16 v[16:31], v[80:83], v[222:225], v[16:31]
	ds_write_b128 v88, v[148:151] offset:8192
	v_add_u32_e32 v80, s16, v183
	ds_write_b128 v80, v[152:155] offset:49152
	ds_write_b128 v80, v[156:159] offset:57344
	s_waitcnt lgkmcnt(4)
	v_mfma_f32_32x32x16_bf16 v[16:31], v[84:87], v[226:229], v[16:31]
	s_cbranch_vccz .LBB0_436
	s_and_saveexec_b64 s[16:17], s[0:1]
	ds_write_b32 v179, v199 offset:128
	s_or_b64 exec, exec, s[16:17]
	s_waitcnt lgkmcnt(0)
	v_add_u32_e32 v92, v177, v176
	ds_read_b128 v[80:83], v92 offset:224
	ds_read_b128 v[84:87], v92 offset:192
	ds_read_b128 v[88:91], v92 offset:160
	ds_read_b128 v[92:95], v92 offset:128
	s_waitcnt lgkmcnt(3)
	v_pk_mul_f32 v[12:13], v[12:13], v[80:81]
	s_waitcnt lgkmcnt(2)
	v_pk_mul_f32 v[8:9], v[8:9], v[84:85]
	s_waitcnt lgkmcnt(1)
	v_pk_mul_f32 v[4:5], v[4:5], v[88:89]
	v_pk_mul_f32 v[14:15], v[14:15], v[82:83]
	v_pk_mul_f32 v[10:11], v[10:11], v[86:87]
	v_pk_mul_f32 v[6:7], v[6:7], v[90:91]
	s_waitcnt lgkmcnt(0)
	v_pk_mul_f32 v[2:3], v[2:3], v[94:95]
	v_pk_mul_f32 v[0:1], v[0:1], v[92:93]
	v_pk_mul_f32 v[60:61], v[60:61], v[80:81]
	v_pk_mul_f32 v[56:57], v[56:57], v[84:85]
	v_pk_mul_f32 v[52:53], v[52:53], v[88:89]
	v_pk_mul_f32 v[62:63], v[62:63], v[82:83]
	v_pk_mul_f32 v[58:59], v[58:59], v[86:87]
	v_pk_mul_f32 v[54:55], v[54:55], v[90:91]
	v_pk_mul_f32 v[50:51], v[50:51], v[94:95]
	v_pk_mul_f32 v[48:49], v[48:49], v[92:93]
	v_pk_mul_f32 v[44:45], v[44:45], v[80:81]
	v_pk_mul_f32 v[40:41], v[40:41], v[84:85]
	v_pk_mul_f32 v[36:37], v[36:37], v[88:89]
	v_pk_mul_f32 v[46:47], v[46:47], v[82:83]
	v_pk_mul_f32 v[42:43], v[42:43], v[86:87]
	v_pk_mul_f32 v[38:39], v[38:39], v[90:91]
	v_pk_mul_f32 v[34:35], v[34:35], v[94:95]
	v_pk_mul_f32 v[32:33], v[32:33], v[92:93]
	v_pk_mul_f32 v[28:29], v[28:29], v[80:81]
	v_pk_mul_f32 v[24:25], v[24:25], v[84:85]
	v_pk_mul_f32 v[20:21], v[20:21], v[88:89]
	v_pk_mul_f32 v[30:31], v[30:31], v[82:83]
	v_pk_mul_f32 v[26:27], v[26:27], v[86:87]
	v_pk_mul_f32 v[22:23], v[22:23], v[90:91]
	v_pk_mul_f32 v[18:19], v[18:19], v[94:95]
	v_pk_mul_f32 v[16:17], v[16:17], v[92:93]
